# deferred PB conversion and w_out/w_pg/w_pp transposes now run only on the workgroups that finish the in-proj phase early (one in-proj unit fewer), so the late workgroups are not delayed
# speedup vs baseline: 1.0186x; 1.0186x over previous
; template <class T, class P> __device__ __forceinline__ T gld_nt(P p) { return __builtin_nontemporal_load((GAS const T*)p); }
; __device__ __forceinline__ u32x2 pk4(f32x4 a) { u32x2 w; w.x = pk2(a[0], a[1]); w.y = pk2(a[2], a[3]); return w; }
; __device__ __forceinline__ void p0_phase(LAS unsigned char* lds, const Args& a, const int w0) {
;     ...
;     const int gt = blockIdx.x * 512 + tid, GT = gridDim.x * 512;
;     for (int i = gt; i < DEPTH * MR * 64; i += 4 * GT) {
;         f32x4 v[4];
; #pragma unroll
;         for (int j = 0; j < 4; ++j) { const int ii = i + j * GT; const int ic = ii < DEPTH * MR * 64 ? ii : i; const int L = ic / (MR * 64), q = ic % (MR * 64), row = q >> 6, c4 = q & 63;
;             const float* src = row < NPR ? a.in[5] + ((size_t)L * NPR + row) * PLE : a.in[6] + ((size_t)L * NSR + row - NPR) * PLE; v[j] = gld_nt<f32x4>(src + c4 * 4); }
; #pragma unroll
;         for (int j = 0; j < 4; ++j) { const int ii = i + j * GT; if (ii < DEPTH * MR * 64) *(u32x2*)((bf16_t*)(ws + WS_PB) + (size_t)ii * 4) = pk4(v[j]); }
;     }
.LBB0_647:
	s_or_b64 exec, exec, s[4:5]
	s_cmp_lt_u32 s40, 64
	s_cbranch_scc1 .Ldp_a_skip
	v_readlane_b32 s28, v255, 16
	v_readlane_b32 s29, v255, 17
	s_cmp_lt_u32 s46, s28
	s_cbranch_scc1 .Ldp_a_skip
	v_readlane_b32 s14, v255, 36
	s_load_dwordx4 s[8:11], s[0:1], 0x28
	s_load_dwordx2 s[12:13], s[0:1], 0x80
	s_cmp_gt_u32 s14, 2
	s_cbranch_scc1 .Ldp_a_skip0
	s_add_i32 s14, s14, 1
	s_mov_b64 s[26:27], exec
	s_sub_i32 s16, s46, s28
	s_mul_i32 s16, s16, 0x1c0
	s_add_i32 s16, s16, s40
	s_add_i32 s16, s16, 0xffffffc0
	v_mbcnt_lo_u32_b32 v0, -1, 0
	v_mbcnt_hi_u32_b32 v0, -1, v0
	s_mul_i32 s17, s29, 0x1c0
	s_mov_b32 s18, 0x100000
	v_add_u32_e32 v0, s16, v0
	s_mul_i32 s19, s17, 4
	s_waitcnt lgkmcnt(0)
	s_lshl_b32 s15, s14, 24
	s_add_u32 s8, s8, s15
	s_addc_u32 s9, s9, 0
	s_lshl_b32 s15, s14, 19
	s_add_u32 s10, s10, s15
	s_addc_u32 s11, s11, 0
	s_mul_i32 s15, s14, 0x840000
	s_add_u32 s12, s12, s15
	s_addc_u32 s13, s13, 0
	s_add_u32 s12, s12, 0x4f00000
	s_addc_u32 s13, s13, 0

; __device__ __forceinline__ void p0_phase(LAS unsigned char* lds, const Args& a, const int w0) {
;     ...
;     for (int it = gw; it < I_IN + 2 * I_SQ + I_PP; it += NGW) {
;         int r = it;
;         if (r < I_IN) { const int L = r / (52 * 16), q = r % (52 * 16), nb = q % 52, kb = q / 52;
;             tr_item64(a.in[8] + (size_t)L * DM * INW, INW, DM, win_src_col(2 * nb), win_src_col(2 * nb + 1), a.in[7] + L * DM, (bf16_t*)(ws + WS_WIN) + (size_t)L * INW * DM, nb * 64, kb * 64, scr, lane); continue; }
;         r -= I_IN;
;         if (r < 2 * I_SQ) { const int which = r / I_SQ; r %= I_SQ; const int L = r / 256, q = r % 256, nb = q & 15, kb = q >> 4;
;             tr_item64(a.in[which ? 12 : 11] + (size_t)L * DM * DM, DM, DM, nb * 64, nb * 64 + 32, nullptr, (bf16_t*)(ws + (which ? WS_WPG : WS_WOUT)) + (size_t)L * DM * DM, nb * 64, kb * 64, scr, lane); continue; }
.Ldp_a_skip:
	s_cmp_lt_u32 s40, 64
	s_cbranch_scc1 .Ldw_w_fin
	v_readlane_b32 s14, v255, 36
	s_load_dwordx4 s[16:19], s[0:1], 0x58
	s_load_dwordx2 s[26:27], s[0:1], 0x68
	s_load_dwordx2 s[28:29], s[0:1], 0x80
	s_lshr_b32 s15, s40, 6
	s_add_i32 s15, s15, -1
	v_readlane_b32 s12, v255, 16
	s_cmp_lt_u32 s46, s12
	s_cbranch_scc1 .Ldw_w_end0
	s_sub_i32 s12, s46, s12
	s_mul_i32 s12, s12, 7
	s_add_i32 s15, s15, s12
	v_mbcnt_lo_u32_b32 v54, -1, 0
	v_mbcnt_hi_u32_b32 v54, -1, v54
	s_waitcnt lgkmcnt(0)

; #define TID_OF(w0) ((w0) * 64 + lane_id())
; #define LAS __attribute__((address_space(3)))
; __device__ __forceinline__ P2Args p2_args() { unsigned char* ws = ka_ws(); return P2Args{(const bf16_t*)(ws + WS_Q), (const bf16_t*)(ws + WS_K), (const bf16_t*)(ws + WS_V), (const bf16_t*)(ws + WS_SGA), (const bf16_t*)(ws + WS_BGC), (const bf16_t*)(ws + WS_U), (bf16_t*)(ws + WS_MIX), ka_in(2), ka_in(3), ka_in(4), ka_in(9), ka_in(10), ka_out()}; }
; __device__ __forceinline__ void p2_phase(LAS unsigned char* lds, const int L, const int w0) {
;     int tid_ = TID_OF(w0); asm volatile("" : "+v"(tid_));
;     const int wid = __builtin_amdgcn_readfirstlane(tid_ >> 6);
;     ...
;     LAS unsigned short* vt = (LAS unsigned short*)(lds + VOFF); LAS unsigned short* svt = (LAS unsigned short*)(lds + SV_OFF);
;     for (int item = blockIdx.x; item < 256; item += gridDim.x) {
;         const P2Args A = p2_args();
;         const int b = item >> 5, n = (item >> 1) & 15, kvh = item & 1, sb = item >> 1;
;         const size_t cb = ((size_t)(L * 128 + sb) * 128) * 128 + kvh * 64;
.Ldw_w_next:
	v_readlane_b32 s15, v55, 0
	v_readlane_b32 s14, v55, 1
	v_readlane_b32 s10, v255, 17
	s_mul_i32 s10, s10, 7
	s_add_i32 s15, s15, s10
	s_branch .Ldw_w_loop
.Ldw_w_end:
	s_branch .Ldw_w_end1
.Ldw_w_end0:
	s_waitcnt lgkmcnt(0)
.Ldw_w_end1:
.Ldw_w_fin:
	s_mov_b64 s[4:5], s[0:1]
	s_waitcnt lgkmcnt(0)
	s_barrier
	v_mbcnt_lo_u32_b32 v0, -1, 0
	v_mbcnt_hi_u32_b32 v0, -1, v0
	s_nop 0
	v_readlane_b32 s4, v255, 7
	v_readlane_b32 s5, v255, 8
	v_add_u32_e32 v154, s40, v0
	s_andn2_b64 vcc, exec, s[4:5]
	v_cndmask_b32_e64 v0, 0, 1, s[4:5]
	v_cmp_ne_u32_e64 s[6:7], 1, v0
	v_readfirstlane_b32 s2, v154
	s_nop 0
	v_writelane_b32 v255, s6, 38
	s_nop 1
	v_writelane_b32 v255, s7, 39
	s_cbranch_vccnz .LBB0_697
	s_ashr_i32 s9, s2, 6
	s_cmp_gt_u32 s2, 63
	s_cselect_b64 s[4:5], -1, 0
	s_ashr_i32 s2, s2, 7
	v_writelane_b32 v255, s2, 40
	s_lshl_b32 s2, s9, 11
	s_add_i32 s8, s2, 0
	s_lshl_b32 s2, s9, 4
	s_lshl_b32 s10, s9, 1
	s_mov_b32 s59, s21
	s_add_i32 s2, s2, -16
	s_add_i32 s6, s10, -2
	s_and_b32 s7, s10, 2
	v_writelane_b32 v255, s2, 41
	s_sub_i32 s9, s10, 18
	s_lshl_b64 s[10:11], s[58:59], 2
	v_writelane_b32 v255, s10, 42
	s_add_i32 s8, s8, 0x1be00
	s_mov_b32 s2, s46
	v_writelane_b32 v255, s11, 43
	s_nop 0
	v_readlane_b32 s10, v255, 18
	v_readlane_b32 s11, v255, 19
	s_branch .LBB0_650
